# layout: attention tile loop head moved to a 64-byte boundary (13 s_nops before the phase), K-loop offsets unchanged
# baseline (speedup 1.0000x reference)
; #define PG8_WAIT_V(n) asm volatile("s_waitcnt vmcnt(" #n ")" ::: "memory")
; #define PG8_BAR __builtin_amdgcn_s_barrier()
; #define AIN(i) arg_in(i)
; template <class Epi, class Sched, bool ALIGN_EPI = false, bool SP2 = false>
; __device__ __forceinline__ void gemm_phase(PG8_LAS unsigned char* lds, const Gemm g, const Sched& S, const Epi& E, const int tid_arg) {
;     ...
;     PG8_WAIT_V(0);
;     if constexpr (!ALIGN_EPI) { if (wr == 0) PG8_BAR; }
;     PG8_BAR;
; __global__ void __launch_bounds__(NTHREADS, 2) fwd_megakernel(Args a) {
;     ...
;             for (int ra_ = 0; ra_ < REP_ATT; ++ra_)
;             for (int bu = bx; bu < nbu; bu += G) {
;                 int lrow, h, t0, qh; bool sample = false; const bf16 *ck = CKB, *cv = CVB;
;                 if (bu < 1024) {
;                     const int sb = bu & 7, j = bu >> 3, hp = (j >> 4) & 7, cp = ((j & 15) + 4 * (j >> 5)) & 15; attn_block_unit(lds, QB, OB, KB, VB, sb, hp, cp, AIN(13), tid); continue; }
.LBB0_451:
	s_waitcnt vmcnt(0)
	s_barrier
	s_nop 0
	s_nop 0
	s_nop 0
	s_nop 0
	s_nop 0
	s_nop 0
	s_nop 0
	s_nop 0
	s_nop 0
	s_nop 0
	s_nop 0
	s_nop 0
	s_nop 0
	s_nop 0
	s_nop 0
	s_nop 0
	s_nop 0
	s_nop 0
	s_nop 0
	s_nop 0
	s_nop 0
	s_nop 0
	s_nop 0
	s_nop 0
	s_nop 0
	s_nop 0
	s_nop 0
	s_nop 0
	s_nop 0
	s_nop 0
	s_nop 0
	s_nop 0
	s_nop 0
	s_nop 0
	s_nop 0
	s_nop 0
	s_nop 0
	s_nop 0
	s_nop 0
	s_nop 0
	s_nop 0
	s_nop 0
	s_nop 0
	s_nop 0
	s_nop 0
	s_nop 0
	s_nop 0
	s_nop 0
	s_nop 0
	s_nop 0
	s_nop 0
	s_nop 0
	s_nop 0
	s_nop 0
	s_nop 0
	s_nop 0
	s_nop 0
	s_nop 0
	s_nop 0
	s_nop 0
	s_nop 0
	s_nop 0
	s_nop 0
	s_nop 0
	s_nop 0
	s_nop 0
	s_nop 0
	s_nop 0
	s_nop 0
	s_nop 0
	s_nop 0
	s_nop 0

; template <class Epi, class Sched, bool ALIGN_EPI = false, bool SP2 = false>
; __device__ __forceinline__ void gemm_phase(PG8_LAS unsigned char* lds, const Gemm g, const Sched& S, const Epi& E, const int tid_arg) {
;     ...
;         const bool has_next = S.next(ui + 1, nxt);
;         const char* nA = has_next ? (const char*)g.A + (size_t)nxt.pm * tstep : cA; const char* nB = has_next ? (const char*)g.Bt + (size_t)nxt.pn * tstep : cB;
;         for (int t = 0; t < nt; t += 2) {
;             const bool last = (t == nt - 2);
;             const char* a1 = cA + (size_t)(t + 1) * kstep;
;             const char* a2 = last ? nA : cA + (size_t)(t + 2) * kstep; const char* b2 = last ? nB : cB + (size_t)(t + 2) * kstep;
;             const char* a3 = a2 + kstep; const char* b3 = b2 + kstep;
;     ...
; #pragma unroll
;         for (int a = 0; a < 2; ++a)
; #pragma unroll
;             for (int b = 0; b < 2; ++b)
; #pragma unroll
;                 for (int m = 0; m < 4; ++m)
; #pragma unroll
;                     for (int n = 0; n < 2; ++n) acc[a][b][m][n] = (f32x4){0.f, 0.f, 0.f, 0.f};
;         cur = nxt; cA = nA; cB = nB; ++ui;
.LBB0_763:
	s_ashr_i32 s27, s26, 31
	s_lshl_b64 s[28:29], s[26:27], 19
	s_add_u32 s28, s3, s28
	s_addc_u32 s29, s6, s29
	s_and_b64 s[30:31], s[10:11], exec
	s_cselect_b32 s27, s29, s5
	s_cselect_b32 s48, s28, s4
	s_ashr_i32 s25, s24, 31
	s_lshl_b64 s[30:31], s[24:25], 19
	s_add_u32 s30, s7, s30
	s_addc_u32 s31, s38, s31
	s_and_b64 s[36:37], s[10:11], exec
	s_cselect_b32 s25, s31, s35
	s_cselect_b32 s49, s30, s34
	s_add_u32 s4, s4, 0x40080
	s_addc_u32 s5, s5, 0
	s_add_u32 s50, s34, 0x100
	v_mov_b32_e32 v4, 0
	s_addc_u32 s51, s35, 0
	s_mov_b32 s52, -2
	v_mov_b32_e32 v5, v4
	v_mov_b32_e32 v6, v4
	v_mov_b32_e32 v7, v4
	v_mov_b32_e32 v8, v4
	v_mov_b32_e32 v9, v4
	v_mov_b32_e32 v10, v4
	v_mov_b32_e32 v11, v4
	v_mov_b32_e32 v20, v4
	v_mov_b32_e32 v21, v4
	v_mov_b32_e32 v22, v4
	v_mov_b32_e32 v23, v4
	v_mov_b32_e32 v24, v4
	v_mov_b32_e32 v25, v4
	v_mov_b32_e32 v26, v4
	v_mov_b32_e32 v27, v4
	v_mov_b32_e32 v36, v4
	v_mov_b32_e32 v37, v4
	v_mov_b32_e32 v38, v4
	v_mov_b32_e32 v39, v4
	v_mov_b32_e32 v40, v4
	v_mov_b32_e32 v41, v4
	v_mov_b32_e32 v42, v4
	v_mov_b32_e32 v43, v4
	v_mov_b32_e32 v52, v4
	v_mov_b32_e32 v53, v4
	v_mov_b32_e32 v54, v4
	v_mov_b32_e32 v55, v4
	v_mov_b32_e32 v56, v4
	v_mov_b32_e32 v57, v4
	v_mov_b32_e32 v58, v4
	v_mov_b32_e32 v59, v4
	v_mov_b32_e32 v12, v4
	v_mov_b32_e32 v13, v4
	v_mov_b32_e32 v14, v4
	v_mov_b32_e32 v15, v4
	v_mov_b32_e32 v16, v4
	v_mov_b32_e32 v17, v4
	v_mov_b32_e32 v18, v4
	v_mov_b32_e32 v19, v4
	v_mov_b32_e32 v28, v4
	v_mov_b32_e32 v29, v4
	v_mov_b32_e32 v30, v4
	v_mov_b32_e32 v31, v4
	v_mov_b32_e32 v32, v4
	v_mov_b32_e32 v33, v4
	v_mov_b32_e32 v34, v4
	v_mov_b32_e32 v35, v4
	v_mov_b32_e32 v44, v4
	v_mov_b32_e32 v45, v4
	v_mov_b32_e32 v46, v4
	v_mov_b32_e32 v47, v4
	v_mov_b32_e32 v48, v4
	v_mov_b32_e32 v49, v4
	v_mov_b32_e32 v50, v4
	v_mov_b32_e32 v51, v4
	v_mov_b32_e32 v60, v4
	v_mov_b32_e32 v61, v4
	v_mov_b32_e32 v62, v4
	v_mov_b32_e32 v63, v4
	v_mov_b32_e32 v64, v4
	v_mov_b32_e32 v65, v4
	v_mov_b32_e32 v66, v4
	v_mov_b32_e32 v67, v4
	v_mov_b32_e32 v68, v4
	v_mov_b32_e32 v69, v4
	v_mov_b32_e32 v70, v4
	v_mov_b32_e32 v71, v4
	v_mov_b32_e32 v72, v4
	v_mov_b32_e32 v73, v4
	v_mov_b32_e32 v74, v4
	v_mov_b32_e32 v75, v4
	v_mov_b32_e32 v84, v4
	v_mov_b32_e32 v85, v4
	v_mov_b32_e32 v86, v4
	v_mov_b32_e32 v87, v4
	v_mov_b32_e32 v88, v4
	v_mov_b32_e32 v89, v4
	v_mov_b32_e32 v90, v4
	v_mov_b32_e32 v91, v4
	v_mov_b32_e32 v100, v4
	v_mov_b32_e32 v101, v4
	v_mov_b32_e32 v102, v4
	v_mov_b32_e32 v103, v4
	v_mov_b32_e32 v104, v4
	v_mov_b32_e32 v105, v4
	v_mov_b32_e32 v106, v4
	v_mov_b32_e32 v107, v4
	v_mov_b32_e32 v116, v4
	v_mov_b32_e32 v117, v4
	v_mov_b32_e32 v118, v4
	v_mov_b32_e32 v119, v4
	s_waitcnt vmcnt(0)
	v_mov_b32_e32 v120, v4
	v_mov_b32_e32 v121, v4
	v_mov_b32_e32 v122, v4
	v_mov_b32_e32 v123, v4
	v_mov_b32_e32 v76, v4
	v_mov_b32_e32 v77, v4
	v_mov_b32_e32 v78, v4
	v_mov_b32_e32 v79, v4
	v_mov_b32_e32 v80, v4
	v_mov_b32_e32 v81, v4
	v_mov_b32_e32 v82, v4
	v_mov_b32_e32 v83, v4
	v_mov_b32_e32 v92, v4
	v_mov_b32_e32 v93, v4
	v_mov_b32_e32 v94, v4
	v_mov_b32_e32 v95, v4
	v_mov_b32_e32 v96, v4
	v_mov_b32_e32 v97, v4
	v_mov_b32_e32 v98, v4
	v_mov_b32_e32 v99, v4
	v_mov_b32_e32 v108, v4
	v_mov_b32_e32 v109, v4
	v_mov_b32_e32 v110, v4
	v_mov_b32_e32 v111, v4
	v_mov_b32_e32 v112, v4
	v_mov_b32_e32 v113, v4
	v_mov_b32_e32 v114, v4
	v_mov_b32_e32 v115, v4
	v_mov_b32_e32 v124, v4
	v_mov_b32_e32 v125, v4
	v_mov_b32_e32 v126, v4
	v_mov_b32_e32 v127, v4
	v_mov_b32_e32 v128, v4
	v_mov_b32_e32 v129, v4
	v_mov_b32_e32 v130, v4
	v_mov_b32_e32 v131, v4
	s_nop 0
	s_nop 0
	s_nop 0
	s_nop 0
	s_nop 0
	s_nop 0
	s_nop 0
	s_nop 0
	s_nop 0
	s_nop 0
	s_nop 0
	s_nop 0
	s_nop 0
	s_nop 0
	s_nop 0
